# full grid barriers: non-leader workgroups poll the top-level generation word directly (one hop less)
# speedup vs baseline: 1.0027x; 1.0023x over previous
; __device__ __forceinline__ unsigned xb_ld(unsigned* p)              { return __hip_atomic_load(p, __ATOMIC_RELAXED, __HIP_MEMORY_SCOPE_AGENT); }
; __device__ __forceinline__ unsigned xb_add(unsigned* p, unsigned v) { return __hip_atomic_fetch_add(p, v, __ATOMIC_RELAXED, __HIP_MEMORY_SCOPE_AGENT); }
; #define XB_SPIN(cond, bar) do { unsigned _sp = 0; while (cond) { __builtin_amdgcn_s_sleep(1); \
;     if ((++_sp & 255u) == 0u) { if (xb_ld(&(bar)[XB_TMO])) break; if (_sp > XB_SPIN_CAP) { atomicAdd(&(bar)[XB_TMO], 1u); break; } } } } while (0)
; __device__ __forceinline__ void xcd_barrier(const XcdBarrier& b) {
;     ...
;         const unsigned old = xb_add(&bar[XB_XSUB(b.x)], 1u);
;         const unsigned gen = old / nloc;
;         if (old + 1u == (gen + 1u) * nloc) {
;             __builtin_amdgcn_fence(__ATOMIC_RELEASE, "agent");
;             asm volatile("s_waitcnt vmcnt(0)" ::: "memory");
;             const unsigned og = xb_add(&bar[XB_TOP], 1u);
;             const unsigned tg = og / nx;
;             if (og + 1u == (tg + 1u) * nx) xb_add(&bar[XB_TOPGEN], 1u);
;             else XB_SPIN(xb_ld(&bar[XB_TOPGEN]) == tg, bar);
;             __builtin_amdgcn_fence(__ATOMIC_ACQUIRE, "agent");
;             xb_add(&bar[XB_XGEN(b.x)], 1u);
;             asm volatile("s_waitcnt vmcnt(0)" ::: "memory");
;         } else {
;             XB_SPIN(xb_ld(&bar[XB_XGEN(b.x)]) == gen, bar);
;             __builtin_amdgcn_fence(__ATOMIC_ACQUIRE, "agent");
;             asm volatile("s_waitcnt vmcnt(0)" ::: "memory");
;         }
.LBB0_44:
	s_or_b64 exec, exec, s[12:13]
	v_cvt_f32_u32_e32 v4, v2
	s_waitcnt vmcnt(0)
	v_readfirstlane_b32 s0, v3
	v_sub_u32_e32 v3, 0, v2
	v_rcp_iflag_f32_e32 v4, v4
	v_add_u32_e32 v5, s0, v1
	v_mul_f32_e32 v4, 0x4f7ffffe, v4
	v_cvt_u32_f32_e32 v4, v4
	v_mul_lo_u32 v1, v3, v4
	v_mul_hi_u32 v1, v4, v1
	v_add_u32_e32 v1, v4, v1
	v_mul_hi_u32 v1, v5, v1
	v_mul_lo_u32 v3, v1, v2
	v_sub_u32_e32 v3, v5, v3
	v_add_u32_e32 v4, 1, v1
	v_cmp_ge_u32_e32 vcc, v3, v2
	s_nop 1
	v_cndmask_b32_e32 v1, v1, v4, vcc
	v_sub_u32_e32 v4, v3, v2
	v_cndmask_b32_e32 v3, v3, v4, vcc
	v_add_u32_e32 v4, 1, v1
	v_cmp_ge_u32_e32 vcc, v3, v2
	v_add_u32_e32 v3, 1, v5
	s_nop 0
	v_cndmask_b32_e32 v1, v1, v4, vcc
	v_mul_lo_u32 v4, v2, v1
	v_add_u32_e32 v2, v4, v2
	v_cmp_ne_u32_e32 vcc, v3, v2
	s_and_saveexec_b64 s[0:1], vcc
	s_xor_b64 s[10:11], exec, s[0:1]
	s_cbranch_execz .LBB0_58
	s_waitcnt lgkmcnt(0)
	s_add_u32 s14, s66, 0x3500
	s_addc_u32 s15, s67, 0
	v_mov_b32_e32 v0, 0
	global_load_dword v0, v0, s[14:15] sc1
	s_waitcnt vmcnt(0)
	v_cmp_eq_u32_e32 vcc, v0, v1
	s_and_saveexec_b64 s[12:13], vcc
	s_cbranch_execz .LBB0_57
	s_mov_b32 s0, 1
	s_mov_b64 s[16:17], 0
	v_mov_b32_e32 v0, 0
	s_branch .LBB0_48

; __device__ __forceinline__ unsigned xb_ld(unsigned* p)              { return __hip_atomic_load(p, __ATOMIC_RELAXED, __HIP_MEMORY_SCOPE_AGENT); }
; __device__ __forceinline__ unsigned xb_add(unsigned* p, unsigned v) { return __hip_atomic_fetch_add(p, v, __ATOMIC_RELAXED, __HIP_MEMORY_SCOPE_AGENT); }
; #define XB_SPIN(cond, bar) do { unsigned _sp = 0; while (cond) { __builtin_amdgcn_s_sleep(1); \
;     if ((++_sp & 255u) == 0u) { if (xb_ld(&(bar)[XB_TMO])) break; if (_sp > XB_SPIN_CAP) { atomicAdd(&(bar)[XB_TMO], 1u); break; } } } } while (0)
; __device__ __forceinline__ void xcd_barrier(const XcdBarrier& b) {
;     ...
;         const unsigned old = xb_add(&bar[XB_XSUB(b.x)], 1u);
;         const unsigned gen = old / nloc;
;         if (old + 1u == (gen + 1u) * nloc) {
;             __builtin_amdgcn_fence(__ATOMIC_RELEASE, "agent");
;             asm volatile("s_waitcnt vmcnt(0)" ::: "memory");
;             const unsigned og = xb_add(&bar[XB_TOP], 1u);
;             const unsigned tg = og / nx;
;             if (og + 1u == (tg + 1u) * nx) xb_add(&bar[XB_TOPGEN], 1u);
;             else XB_SPIN(xb_ld(&bar[XB_TOPGEN]) == tg, bar);
;             __builtin_amdgcn_fence(__ATOMIC_ACQUIRE, "agent");
;             xb_add(&bar[XB_XGEN(b.x)], 1u);
;             asm volatile("s_waitcnt vmcnt(0)" ::: "memory");
;         } else {
;             XB_SPIN(xb_ld(&bar[XB_XGEN(b.x)]) == gen, bar);
;             __builtin_amdgcn_fence(__ATOMIC_ACQUIRE, "agent");
;             asm volatile("s_waitcnt vmcnt(0)" ::: "memory");
;         }
.LBB0_470:
	s_or_b64 exec, exec, s[12:13]
	v_cvt_f32_u32_e32 v4, v2
	s_waitcnt vmcnt(0)
	v_readfirstlane_b32 s1, v3
	v_sub_u32_e32 v3, 0, v2
	v_rcp_iflag_f32_e32 v4, v4
	v_add_u32_e32 v5, s1, v1
	v_mul_f32_e32 v4, 0x4f7ffffe, v4
	v_cvt_u32_f32_e32 v4, v4
	v_mul_lo_u32 v1, v3, v4
	v_mul_hi_u32 v1, v4, v1
	v_add_u32_e32 v1, v4, v1
	v_mul_hi_u32 v1, v5, v1
	v_mul_lo_u32 v3, v1, v2
	v_sub_u32_e32 v3, v5, v3
	v_add_u32_e32 v4, 1, v1
	v_cmp_ge_u32_e32 vcc, v3, v2
	s_nop 1
	v_cndmask_b32_e32 v1, v1, v4, vcc
	v_sub_u32_e32 v4, v3, v2
	v_cndmask_b32_e32 v3, v3, v4, vcc
	v_add_u32_e32 v4, 1, v1
	v_cmp_ge_u32_e32 vcc, v3, v2
	v_add_u32_e32 v3, 1, v5
	s_nop 0
	v_cndmask_b32_e32 v1, v1, v4, vcc
	v_mul_lo_u32 v4, v2, v1
	v_add_u32_e32 v2, v4, v2
	v_cmp_ne_u32_e32 vcc, v3, v2
	s_and_saveexec_b64 s[10:11], vcc
	s_xor_b64 s[10:11], exec, s[10:11]
	s_cbranch_execz .LBB0_484
	s_waitcnt lgkmcnt(0)
	s_add_u32 s14, s66, 0x3500
	s_addc_u32 s15, s67, 0
	v_mov_b32_e32 v0, 0
	global_load_dword v0, v0, s[14:15] sc1
	s_waitcnt vmcnt(0)
	v_cmp_eq_u32_e32 vcc, v0, v1
	s_and_saveexec_b64 s[12:13], vcc
	s_cbranch_execz .LBB0_483
	s_mov_b32 s1, 1
	s_mov_b64 s[16:17], 0
	v_mov_b32_e32 v0, 0
	s_branch .LBB0_474
